# grid barrier: non-leader workgroups poll the cross-XCD generation word directly instead of the per-XCD relay (one polling hop less)
# speedup vs baseline: 1.0383x; 1.0168x over previous
.LBB0_55:
	s_or_b64 exec, exec, s[8:9]
	v_cvt_f32_u32_e32 v4, v2
	s_waitcnt vmcnt(0)
	v_readfirstlane_b32 s0, v3
	v_sub_u32_e32 v3, 0, v2
	v_rcp_iflag_f32_e32 v4, v4
	v_add_u32_e32 v5, s0, v1
	v_mul_f32_e32 v4, 0x4f7ffffe, v4
	v_cvt_u32_f32_e32 v4, v4
	v_mul_lo_u32 v1, v3, v4
	v_mul_hi_u32 v1, v4, v1
	v_add_u32_e32 v1, v4, v1
	v_mul_hi_u32 v1, v5, v1
	v_mul_lo_u32 v3, v1, v2
	v_sub_u32_e32 v3, v5, v3
	v_add_u32_e32 v4, 1, v1
	v_cmp_ge_u32_e32 vcc, v3, v2
	s_nop 1
	v_cndmask_b32_e32 v1, v1, v4, vcc
	v_sub_u32_e32 v4, v3, v2
	v_cndmask_b32_e32 v3, v3, v4, vcc
	v_add_u32_e32 v4, 1, v1
	v_cmp_ge_u32_e32 vcc, v3, v2
	v_add_u32_e32 v3, 1, v5
	s_nop 0
	v_cndmask_b32_e32 v1, v1, v4, vcc
	v_mul_lo_u32 v4, v2, v1
	v_add_u32_e32 v2, v4, v2
	v_cmp_ne_u32_e32 vcc, v3, v2
	s_and_saveexec_b64 s[0:1], vcc
	s_xor_b64 s[6:7], exec, s[0:1]
	s_cbranch_execz .LBB0_69
	s_waitcnt lgkmcnt(0)
	s_add_u32 s16, s92, 0x4500
	s_addc_u32 s17, s93, 0
	v_mov_b32_e32 v0, 0
	global_load_dword v0, v0, s[16:17] sc1
	s_waitcnt vmcnt(0)
	v_cmp_eq_u32_e32 vcc, v0, v1
	s_and_saveexec_b64 s[8:9], vcc
	s_cbranch_execz .LBB0_68
	s_add_u32 s14, s92, 0x1200
	s_addc_u32 s15, s93, 0
	s_mov_b32 s0, 1
	s_mov_b64 s[18:19], 0
	v_mov_b32_e32 v0, 0
	s_branch .LBB0_59

.LBB0_311:
	s_or_b64 exec, exec, s[8:9]
	v_cvt_f32_u32_e32 v4, v2
	s_waitcnt vmcnt(0)
	v_readfirstlane_b32 s0, v3
	v_sub_u32_e32 v3, 0, v2
	v_rcp_iflag_f32_e32 v4, v4
	v_add_u32_e32 v5, s0, v1
	v_mul_f32_e32 v4, 0x4f7ffffe, v4
	v_cvt_u32_f32_e32 v4, v4
	v_mul_lo_u32 v1, v3, v4
	v_mul_hi_u32 v1, v4, v1
	v_add_u32_e32 v1, v4, v1
	v_mul_hi_u32 v1, v5, v1
	v_mul_lo_u32 v3, v1, v2
	v_sub_u32_e32 v3, v5, v3
	v_add_u32_e32 v4, 1, v1
	v_cmp_ge_u32_e32 vcc, v3, v2
	s_nop 1
	v_cndmask_b32_e32 v1, v1, v4, vcc
	v_sub_u32_e32 v4, v3, v2
	v_cndmask_b32_e32 v3, v3, v4, vcc
	v_add_u32_e32 v4, 1, v1
	v_cmp_ge_u32_e32 vcc, v3, v2
	v_add_u32_e32 v3, 1, v5
	s_nop 0
	v_cndmask_b32_e32 v1, v1, v4, vcc
	v_mul_lo_u32 v4, v2, v1
	v_add_u32_e32 v2, v4, v2
	v_cmp_ne_u32_e32 vcc, v3, v2
	s_and_saveexec_b64 s[0:1], vcc
	s_xor_b64 s[6:7], exec, s[0:1]
	s_cbranch_execz .LBB0_325
	s_waitcnt lgkmcnt(0)
	s_add_u32 s14, s92, 0x4500
	s_addc_u32 s15, s93, 0
	v_mov_b32_e32 v0, 0
	global_load_dword v0, v0, s[14:15] sc1
	s_waitcnt vmcnt(0)
	v_cmp_eq_u32_e32 vcc, v0, v1
	s_and_saveexec_b64 s[8:9], vcc
	s_cbranch_execz .LBB0_324
	s_add_u32 s12, s92, 0x1200
	s_addc_u32 s13, s93, 0
	s_mov_b32 s0, 1
	s_mov_b64 s[16:17], 0
	v_mov_b32_e32 v0, 0
	s_branch .LBB0_315

.LBB0_677:
	s_or_b64 exec, exec, s[10:11]
	v_cvt_f32_u32_e32 v4, v2
	s_waitcnt vmcnt(0)
	v_readfirstlane_b32 s0, v3
	v_sub_u32_e32 v3, 0, v2
	v_rcp_iflag_f32_e32 v4, v4
	v_add_u32_e32 v5, s0, v1
	v_mul_f32_e32 v4, 0x4f7ffffe, v4
	v_cvt_u32_f32_e32 v4, v4
	v_mul_lo_u32 v1, v3, v4
	v_mul_hi_u32 v1, v4, v1
	v_add_u32_e32 v1, v4, v1
	v_mul_hi_u32 v1, v5, v1
	v_mul_lo_u32 v3, v1, v2
	v_sub_u32_e32 v3, v5, v3
	v_add_u32_e32 v4, 1, v1
	v_cmp_ge_u32_e32 vcc, v3, v2
	s_nop 1
	v_cndmask_b32_e32 v1, v1, v4, vcc
	v_sub_u32_e32 v4, v3, v2
	v_cndmask_b32_e32 v3, v3, v4, vcc
	v_add_u32_e32 v4, 1, v1
	v_cmp_ge_u32_e32 vcc, v3, v2
	v_add_u32_e32 v3, 1, v5
	s_nop 0
	v_cndmask_b32_e32 v1, v1, v4, vcc
	v_mul_lo_u32 v4, v2, v1
	v_add_u32_e32 v2, v4, v2
	v_cmp_ne_u32_e32 vcc, v3, v2
	s_and_saveexec_b64 s[0:1], vcc
	s_xor_b64 s[8:9], exec, s[0:1]
	s_cbranch_execz .LBB0_691
	s_waitcnt lgkmcnt(0)
	s_add_u32 s12, s66, 0x4500
	s_addc_u32 s13, s67, 0
	v_mov_b32_e32 v0, 0
	global_load_dword v0, v0, s[12:13] sc1
	s_waitcnt vmcnt(0)
	v_cmp_eq_u32_e32 vcc, v0, v1
	s_and_saveexec_b64 s[10:11], vcc
	s_cbranch_execz .LBB0_690
	s_mov_b32 s0, 1
	s_mov_b64 s[14:15], 0
	v_mov_b32_e32 v0, 0
	s_branch .LBB0_681
